# MLA FAST tile loop rewritten by hand: PV-first periods (barrier, PV(t-1), QK(t)), single S buffer, 7-deep rolling K/R/V fragment rings, SALU-formed DMA addresses, deferred cross-half row-sum
# speedup vs baseline: 1.1505x; 1.0283x over previous
.LBB0_807:
	v_mov_b32_e32 v96, v0
	v_mov_b32_e32 v97, v1
	v_mov_b32_e32 v98, v2
	v_mov_b32_e32 v99, v3
	v_mov_b32_e32 v100, v4
	v_mov_b32_e32 v101, v5
	v_mov_b32_e32 v102, v6
	v_mov_b32_e32 v103, v7
	v_mov_b32_e32 v104, v8
	v_mov_b32_e32 v105, v9
	v_mov_b32_e32 v106, v10
	v_mov_b32_e32 v107, v11
	v_mov_b32_e32 v108, v12
	v_mov_b32_e32 v109, v13
	v_mov_b32_e32 v110, v14
	v_mov_b32_e32 v111, v15
	v_add_u32_e32 v2, s36, v20
	v_mov_b64_e32 v[0:1], s[8:9]
	v_mad_i64_i32 v[0:1], s[36:37], v2, s89, v[0:1]
	v_and_b32_e32 v2, 7, v21
	s_add_u32 s36, s27, s92
	v_lshlrev_b32_e32 v2, 4, v2
	v_mov_b32_e32 v3, v147
	s_addc_u32 s37, 0, 0
	s_add_i32 s21, s21, s20
	v_lshl_add_u64 v[150:151], v[0:1], 0, v[2:3]
	v_add3_u32 v0, s21, v19, v18
	v_ashrrev_i32_e32 v1, 31, v0
	v_lshlrev_b64 v[0:1], 12, v[0:1]
	v_and_b32_e32 v2, 3, v16
	s_lshl_b32 s8, s0, 1
	v_lshl_add_u64 v[0:1], s[36:37], 0, v[0:1]
	v_lshlrev_b32_e32 v2, 4, v2
	s_and_b32 s8, s8, 0x80
	v_lshl_add_u64 v[0:1], v[0:1], 0, v[2:3]
	v_lshl_or_b32 v2, v163, 6, s8
	v_lshl_add_u64 v[152:153], v[0:1], 0, v[2:3]
	v_add_u32_e32 v0, s19, v17
	v_ashrrev_i32_e32 v1, 31, v0
	v_lshlrev_b64 v[0:1], 12, v[0:1]
	v_lshl_add_u64 v[0:1], s[36:37], 0, v[0:1]
	v_lshl_add_u64 v[154:155], v[0:1], 0, v[146:147]
	v_and_b32_e32 v149, 63, v16
	v_lshlrev_b32_e32 v0, 4, v162
	v_lshlrev_b32_e32 v23, 8, v162
	v_and_b32_e32 v52, 0xf0, v0
	v_or_b32_e32 v24, 0x0, v148
	v_xor_b32_e32 v24, v24, v52
	v_or_b32_e32 v24, v24, v23
	v_add_u32_e32 v242, 0xc000, v24
	v_or_b32_e32 v24, 0x20, v148
	v_xor_b32_e32 v24, v24, v52
	v_or_b32_e32 v24, v24, v23
	v_add_u32_e32 v243, 0xc000, v24
	v_or_b32_e32 v24, 0x40, v148
	v_xor_b32_e32 v24, v24, v52
	v_or_b32_e32 v24, v24, v23
	v_add_u32_e32 v244, 0xc000, v24
	v_or_b32_e32 v24, 0x60, v148
	v_xor_b32_e32 v24, v24, v52
	v_or_b32_e32 v24, v24, v23
	v_add_u32_e32 v245, 0xc000, v24
	v_or_b32_e32 v24, 0x80, v148
	v_xor_b32_e32 v24, v24, v52
	v_or_b32_e32 v24, v24, v23
	v_add_u32_e32 v246, 0xc000, v24
	v_or_b32_e32 v24, 0xa0, v148
	v_xor_b32_e32 v24, v24, v52
	v_or_b32_e32 v24, v24, v23
	v_add_u32_e32 v247, 0xc000, v24
	v_or_b32_e32 v24, 0xc0, v148
	v_xor_b32_e32 v24, v24, v52
	v_or_b32_e32 v24, v24, v23
	v_add_u32_e32 v248, 0xc000, v24
	v_or_b32_e32 v24, 0xe0, v148
	v_xor_b32_e32 v24, v24, v52
	v_or_b32_e32 v24, v24, v23
	v_add_u32_e32 v249, 0xc000, v24
	v_lshlrev_b32_e32 v25, 7, v162
	v_bfe_u32 v26, v16, 1, 3
	v_or_b32_e32 v24, 0, v163
	v_xor_b32_e32 v24, v24, v26
	v_lshl_or_b32 v24, v24, 4, v25
	v_add_u32_e32 v250, 0x14000, v24
	v_or_b32_e32 v24, 2, v163
	v_xor_b32_e32 v24, v24, v26
	v_lshl_or_b32 v24, v24, 4, v25
	v_add_u32_e32 v251, 0x14000, v24
	v_or_b32_e32 v24, 4, v163
	v_xor_b32_e32 v24, v24, v26
	v_lshl_or_b32 v24, v24, 4, v25
	v_add_u32_e32 v252, 0x14000, v24
	v_or_b32_e32 v24, 6, v163
	v_xor_b32_e32 v24, v24, v26
	v_lshl_or_b32 v24, v24, 4, v25
	v_add_u32_e32 v253, 0x14000, v24
	v_lshlrev_b32_e32 v24, 4, v149
	v_lshlrev_b32_e32 v25, 3, v149
	v_and_b32_e32 v26, 0xc0, v24
	v_and_or_b32 v24, v25, 24, v26
	v_lshlrev_b32_e32 v26, 1, v149
	v_and_b32_e32 v26, 32, v26
	v_and_b32_e32 v25, 0x100, v25
	v_or3_b32 v165, v24, v26, v25
	v_mov_b32_e32 v166, v165
	s_mov_b32 s14, 0x8000
	s_add_i32 s38, s5, 0x2000
	s_movk_i32 s15, 63
	v_mov_b32_e32 v0, 0
	v_mov_b32_e32 v1, 0
	v_mov_b32_e32 v2, 0
	v_mov_b32_e32 v3, 0
	v_mov_b32_e32 v4, 0
	v_mov_b32_e32 v5, 0
	v_mov_b32_e32 v6, 0
	v_mov_b32_e32 v7, 0
	v_mov_b32_e32 v8, 0
	v_mov_b32_e32 v9, 0
	v_mov_b32_e32 v10, 0
	v_mov_b32_e32 v11, 0
	v_mov_b32_e32 v12, 0
	v_mov_b32_e32 v13, 0
	v_mov_b32_e32 v14, 0
	v_mov_b32_e32 v15, 0
	v_mov_b32_e32 v16, 0
	v_mov_b32_e32 v17, 0
	v_mov_b32_e32 v18, 0
	v_mov_b32_e32 v19, 0
	v_mov_b32_e32 v20, 0
	v_mov_b32_e32 v21, 0
	v_mov_b32_e32 v22, 0
	v_mov_b32_e32 v23, 0
	v_mov_b32_e32 v24, 0
	v_mov_b32_e32 v25, 0
	v_mov_b32_e32 v26, 0
	v_mov_b32_e32 v27, 0
	v_mov_b32_e32 v28, 0
	v_mov_b32_e32 v29, 0
	v_mov_b32_e32 v30, 0
	v_mov_b32_e32 v31, 0
	v_mov_b32_e32 v32, 0
	v_mov_b32_e32 v33, 0
	v_mov_b32_e32 v34, 0
	v_mov_b32_e32 v35, 0
	v_mov_b32_e32 v36, 0
	v_mov_b32_e32 v37, 0
	v_mov_b32_e32 v38, 0
	v_mov_b32_e32 v39, 0
	v_mov_b32_e32 v40, 0
	v_mov_b32_e32 v41, 0
	v_mov_b32_e32 v42, 0
	v_mov_b32_e32 v43, 0
	v_mov_b32_e32 v44, 0
	v_mov_b32_e32 v45, 0
	v_mov_b32_e32 v46, 0
	v_mov_b32_e32 v47, 0
	v_mov_b32_e32 v48, 0
	v_mov_b32_e32 v49, 0
	v_mov_b32_e32 v50, 0
	v_mov_b32_e32 v51, 0
	v_mov_b32_e32 v52, 0
	v_mov_b32_e32 v53, 0
	v_mov_b32_e32 v54, 0
	v_mov_b32_e32 v55, 0
	v_mov_b32_e32 v56, 0
	v_mov_b32_e32 v57, 0
	v_mov_b32_e32 v58, 0
	v_mov_b32_e32 v59, 0
	v_mov_b32_e32 v60, 0
	v_mov_b32_e32 v61, 0
	v_mov_b32_e32 v62, 0
	v_mov_b32_e32 v63, 0
	v_mov_b32_e32 v254, 0
	v_mov_b32_e32 v255, 0
	s_waitcnt lgkmcnt(0)
	s_waitcnt vmcnt(0)
	s_barrier
	ds_read_b128 v[184:187], v242 offset:0
	ds_read_b128 v[188:191], v243 offset:0
	s_add_i32 s14, s14, 0x4000
	s_cmp_ge_u32 s14, 0xc000
	s_cselect_b32 s18, 0xc000, 0
	s_sub_i32 s14, s14, s18
	v_add_u32_e32 v166, s14, v165
	ds_read_b128 v[192:195], v244 offset:0
	ds_read_b128 v[196:199], v245 offset:0
	ds_read_b128 v[200:203], v246 offset:0
	ds_read_b128 v[204:207], v247 offset:0
	ds_read_b128 v[208:211], v248 offset:0
	s_waitcnt lgkmcnt(6)
	v_mfma_f32_32x32x16_bf16 v[64:79], v[184:187], v[140:143], 0
	ds_read_b128 v[184:187], v249 offset:0
	s_waitcnt lgkmcnt(6)
	v_mfma_f32_32x32x16_bf16 v[64:79], v[188:191], v[136:139], v[64:79]
	ds_read_b128 v[188:191], v250 offset:0
	s_waitcnt lgkmcnt(6)
	v_mfma_f32_32x32x16_bf16 v[64:79], v[192:195], v[132:135], v[64:79]
	ds_read_b128 v[192:195], v251 offset:0
	s_waitcnt lgkmcnt(6)
	v_mfma_f32_32x32x16_bf16 v[64:79], v[196:199], v[128:131], v[64:79]
	ds_read_b128 v[196:199], v252 offset:0
	s_waitcnt lgkmcnt(6)
	v_mfma_f32_32x32x16_bf16 v[64:79], v[200:203], v[124:127], v[64:79]
	ds_read_b128 v[200:203], v253 offset:0
	s_waitcnt lgkmcnt(6)
	v_mfma_f32_32x32x16_bf16 v[64:79], v[204:207], v[120:123], v[64:79]
	ds_read_b128 v[204:207], v242 offset:8192
	s_waitcnt lgkmcnt(6)
	v_mfma_f32_32x32x16_bf16 v[64:79], v[208:211], v[116:119], v[64:79]
	ds_read_b128 v[208:211], v243 offset:8192
	s_waitcnt lgkmcnt(6)
	v_mfma_f32_32x32x16_bf16 v[64:79], v[184:187], v[112:115], v[64:79]
	ds_read_b128 v[184:187], v244 offset:8192
	s_waitcnt lgkmcnt(6)
	v_mfma_f32_32x32x16_bf16 v[64:79], v[188:191], v[96:99], v[64:79]
	ds_read_b128 v[188:191], v245 offset:8192
	s_waitcnt lgkmcnt(6)
	v_mfma_f32_32x32x16_bf16 v[64:79], v[192:195], v[100:103], v[64:79]
	ds_read_b128 v[192:195], v246 offset:8192
	s_waitcnt lgkmcnt(6)
	v_mfma_f32_32x32x16_bf16 v[64:79], v[196:199], v[104:107], v[64:79]
	ds_read_b128 v[196:199], v247 offset:8192
	s_waitcnt lgkmcnt(6)
	v_mfma_f32_32x32x16_bf16 v[64:79], v[200:203], v[108:111], v[64:79]
	ds_read_b128 v[200:203], v248 offset:8192
	s_waitcnt lgkmcnt(6)
	v_mfma_f32_32x32x16_bf16 v[80:95], v[204:207], v[140:143], 0
	ds_read_b128 v[204:207], v249 offset:8192
	s_waitcnt lgkmcnt(6)
	v_mfma_f32_32x32x16_bf16 v[80:95], v[208:211], v[136:139], v[80:95]
	ds_read_b128 v[208:211], v250 offset:4096
	s_waitcnt lgkmcnt(6)
	v_mfma_f32_32x32x16_bf16 v[80:95], v[184:187], v[132:135], v[80:95]
	ds_read_b128 v[184:187], v251 offset:4096
	s_waitcnt lgkmcnt(6)
	v_mfma_f32_32x32x16_bf16 v[80:95], v[188:191], v[128:131], v[80:95]
	v_exp_f32_e32 v64, v64
	v_exp_f32_e32 v65, v65
	v_exp_f32_e32 v66, v66
	ds_read_b128 v[188:191], v252 offset:4096
	s_waitcnt lgkmcnt(6)
	v_mfma_f32_32x32x16_bf16 v[80:95], v[192:195], v[124:127], v[80:95]
	v_exp_f32_e32 v67, v67
	v_add_f32_e32 v254, v254, v64
	v_exp_f32_e32 v68, v68
	v_add_f32_e32 v255, v255, v65
	ds_read_b128 v[192:195], v253 offset:4096
	s_waitcnt lgkmcnt(6)
	v_mfma_f32_32x32x16_bf16 v[80:95], v[196:199], v[120:123], v[80:95]
	v_exp_f32_e32 v69, v69
	v_add_f32_e32 v254, v254, v66
	v_exp_f32_e32 v70, v70
	ds_read_b64_tr_b16 v[212:213], v166 offset:0
	ds_read_b64_tr_b16 v[214:215], v166 offset:2048
	s_waitcnt lgkmcnt(7)
	v_mfma_f32_32x32x16_bf16 v[80:95], v[200:203], v[116:119], v[80:95]
	v_add_f32_e32 v255, v255, v67
	v_exp_f32_e32 v71, v71
	v_add_f32_e32 v254, v254, v68
	v_add_f32_e32 v255, v255, v69
	v_add_f32_e32 v254, v254, v70
	ds_read_b64_tr_b16 v[216:217], v166 offset:512
	ds_read_b64_tr_b16 v[218:219], v166 offset:2560
	s_waitcnt lgkmcnt(8)
	v_mfma_f32_32x32x16_bf16 v[80:95], v[204:207], v[112:115], v[80:95]
	v_add_f32_e32 v255, v255, v71
	v_cvt_pk_bf16_f32 v168, v64, v65
	v_cvt_pk_bf16_f32 v170, v68, v69
	v_cvt_pk_bf16_f32 v169, v66, v67
	v_cvt_pk_bf16_f32 v171, v70, v71
	ds_read_b64_tr_b16 v[220:221], v166 offset:1024
	ds_read_b64_tr_b16 v[222:223], v166 offset:3072
	s_waitcnt lgkmcnt(9)
	v_mfma_f32_32x32x16_bf16 v[80:95], v[208:211], v[96:99], v[80:95]
	v_exp_f32_e32 v72, v72
	v_exp_f32_e32 v73, v73
	v_exp_f32_e32 v74, v74
	v_exp_f32_e32 v75, v75
	ds_read_b64_tr_b16 v[224:225], v166 offset:1536
	ds_read_b64_tr_b16 v[226:227], v166 offset:3584
	s_waitcnt lgkmcnt(10)
	v_mfma_f32_32x32x16_bf16 v[80:95], v[184:187], v[100:103], v[80:95]
	v_add_f32_e32 v254, v254, v72
	v_exp_f32_e32 v76, v76
	v_add_f32_e32 v255, v255, v73
	v_exp_f32_e32 v77, v77
	ds_read_b64_tr_b16 v[228:229], v166 offset:4096
	ds_read_b64_tr_b16 v[230:231], v166 offset:6144
	s_waitcnt lgkmcnt(11)
	v_mfma_f32_32x32x16_bf16 v[80:95], v[188:191], v[104:107], v[80:95]
	v_add_f32_e32 v254, v254, v74
	v_exp_f32_e32 v78, v78
	v_add_f32_e32 v255, v255, v75
	v_exp_f32_e32 v79, v79
	v_add_f32_e32 v254, v254, v76
	ds_read_b64_tr_b16 v[232:233], v166 offset:4608
	ds_read_b64_tr_b16 v[234:235], v166 offset:6656
	s_waitcnt lgkmcnt(12)
	v_mfma_f32_32x32x16_bf16 v[80:95], v[192:195], v[108:111], v[80:95]
	v_add_f32_e32 v255, v255, v77
	v_add_f32_e32 v254, v254, v78
	v_add_f32_e32 v255, v255, v79
	v_cvt_pk_bf16_f32 v172, v72, v73
	v_cvt_pk_bf16_f32 v174, v76, v77
	v_cvt_pk_bf16_f32 v173, v74, v75
	v_cvt_pk_bf16_f32 v175, v78, v79
.Lmla_loop:
	s_waitcnt vmcnt(0)
	s_barrier
	s_add_i32 s37, s14, 0x8000
	s_cmp_ge_u32 s37, 0xc000
	s_cselect_b32 s18, 0xc000, 0
	s_sub_i32 s37, s37, s18
	ds_read_b64_tr_b16 v[238:239], v166 offset:5120
	ds_read_b64_tr_b16 v[240:241], v166 offset:7168
	s_add_i32 m0, s5, 0xc000
	s_add_u32 s46, s28, s64
	s_addc_u32 s47, s29, s65
	global_load_lds_dwordx4 v154, s[46:47]
	s_waitcnt lgkmcnt(12)
	v_mfma_f32_32x32x16_bf16 v[48:63], v[168:171], v[212:215], v[48:63]
	v_exp_f32_e32 v80, v80
	v_exp_f32_e32 v81, v81
	v_exp_f32_e32 v82, v82
	ds_read_b64_tr_b16 v[212:213], v166 offset:5632
	ds_read_b64_tr_b16 v[214:215], v166 offset:7680
	s_add_i32 m0, s5, 0xe000
	s_add_u32 s46, s28, s66
	s_addc_u32 s47, s29, s67
	global_load_lds_dwordx4 v154, s[46:47]
	s_waitcnt lgkmcnt(12)
	v_mfma_f32_32x32x16_bf16 v[32:47], v[168:171], v[216:219], v[32:47]
	v_exp_f32_e32 v83, v83
	v_add_f32_e32 v254, v254, v80
	v_exp_f32_e32 v84, v84
	v_add_f32_e32 v255, v255, v81
	ds_read_b64_tr_b16 v[216:217], v166 offset:8192
	ds_read_b64_tr_b16 v[218:219], v166 offset:10240
	s_add_i32 m0, s5, s37
	s_add_u32 s46, s28, s68
	s_addc_u32 s47, s29, s69
	global_load_lds_dwordx4 v152, s[46:47]
	s_waitcnt lgkmcnt(12)
	v_mfma_f32_32x32x16_bf16 v[16:31], v[168:171], v[220:223], v[16:31]
	v_exp_f32_e32 v85, v85
	v_add_f32_e32 v254, v254, v82
	v_exp_f32_e32 v86, v86
	ds_read_b64_tr_b16 v[220:221], v166 offset:8704
	ds_read_b64_tr_b16 v[222:223], v166 offset:10752
	s_add_i32 m0, s37, s38
	s_add_u32 s46, s28, s70
	s_addc_u32 s47, s29, s71
	global_load_lds_dwordx4 v152, s[46:47]
	s_waitcnt lgkmcnt(12)
	v_mfma_f32_32x32x16_bf16 v[0:15], v[168:171], v[224:227], v[0:15]
	v_add_f32_e32 v255, v255, v83
	v_exp_f32_e32 v87, v87
	v_add_f32_e32 v254, v254, v84
	v_add_f32_e32 v255, v255, v85
	v_add_f32_e32 v254, v254, v86
	ds_read_b64_tr_b16 v[224:225], v166 offset:9216
	ds_read_b64_tr_b16 v[226:227], v166 offset:11264
	s_add_i32 m0, s5, 0x14000
	s_add_u32 s46, s28, s72
	s_addc_u32 s47, s29, s73
	global_load_lds_dwordx4 v150, s[46:47]
	s_waitcnt lgkmcnt(12)
	v_mfma_f32_32x32x16_bf16 v[48:63], v[172:175], v[228:231], v[48:63]
	v_add_f32_e32 v255, v255, v87
	v_cvt_pk_bf16_f32 v176, v80, v81
	v_cvt_pk_bf16_f32 v178, v84, v85
	v_cvt_pk_bf16_f32 v177, v82, v83
	v_cvt_pk_bf16_f32 v179, v86, v87
	ds_read_b64_tr_b16 v[228:229], v166 offset:9728
	ds_read_b64_tr_b16 v[230:231], v166 offset:11776
	s_waitcnt lgkmcnt(12)
	v_mfma_f32_32x32x16_bf16 v[32:47], v[172:175], v[232:235], v[32:47]
	v_exp_f32_e32 v88, v88
	v_exp_f32_e32 v89, v89
	v_exp_f32_e32 v90, v90
	ds_read_b64_tr_b16 v[232:233], v166 offset:12288
	ds_read_b64_tr_b16 v[234:235], v166 offset:14336
	s_waitcnt lgkmcnt(12)
	v_mfma_f32_32x32x16_bf16 v[16:31], v[172:175], v[238:241], v[16:31]
	v_exp_f32_e32 v91, v91
	v_add_f32_e32 v254, v254, v88
	v_exp_f32_e32 v92, v92
	ds_read_b64_tr_b16 v[238:239], v166 offset:12800
	ds_read_b64_tr_b16 v[240:241], v166 offset:14848
	s_waitcnt lgkmcnt(12)
	v_mfma_f32_32x32x16_bf16 v[0:15], v[172:175], v[212:215], v[0:15]
	v_add_f32_e32 v255, v255, v89
	v_exp_f32_e32 v93, v93
	ds_read_b64_tr_b16 v[212:213], v166 offset:13312
	ds_read_b64_tr_b16 v[214:215], v166 offset:15360
	s_waitcnt lgkmcnt(12)
	v_mfma_f32_32x32x16_bf16 v[48:63], v[176:179], v[216:219], v[48:63]
	v_add_f32_e32 v254, v254, v90
	v_exp_f32_e32 v94, v94
	v_add_f32_e32 v255, v255, v91
	v_exp_f32_e32 v95, v95
	ds_read_b64_tr_b16 v[216:217], v166 offset:13824
	ds_read_b64_tr_b16 v[218:219], v166 offset:15872
	s_waitcnt lgkmcnt(12)
	v_mfma_f32_32x32x16_bf16 v[32:47], v[176:179], v[220:223], v[32:47]
	v_add_f32_e32 v254, v254, v92
	v_add_f32_e32 v255, v255, v93
	v_add_f32_e32 v254, v254, v94
	v_add_f32_e32 v255, v255, v95
	ds_read_b128 v[184:187], v242 offset:16384
	s_waitcnt lgkmcnt(11)
	v_mfma_f32_32x32x16_bf16 v[16:31], v[176:179], v[224:227], v[16:31]
	v_cvt_pk_bf16_f32 v180, v88, v89
	v_cvt_pk_bf16_f32 v182, v92, v93
	v_cvt_pk_bf16_f32 v181, v90, v91
	v_cvt_pk_bf16_f32 v183, v94, v95
	ds_read_b128 v[188:191], v243 offset:16384
	s_waitcnt lgkmcnt(10)
	v_mfma_f32_32x32x16_bf16 v[0:15], v[176:179], v[228:231], v[0:15]
	s_add_i32 s14, s14, 0x4000
	s_cmp_ge_u32 s14, 0xc000
	s_cselect_b32 s18, 0xc000, 0
	s_sub_i32 s14, s14, s18
	v_add_u32_e32 v166, s14, v165
	ds_read_b128 v[192:195], v244 offset:16384
	s_waitcnt lgkmcnt(9)
	v_mfma_f32_32x32x16_bf16 v[48:63], v[180:183], v[232:235], v[48:63]
	ds_read_b128 v[196:199], v245 offset:16384
	s_waitcnt lgkmcnt(8)
	v_mfma_f32_32x32x16_bf16 v[32:47], v[180:183], v[238:241], v[32:47]
	ds_read_b128 v[200:203], v246 offset:16384
	s_waitcnt lgkmcnt(7)
	v_mfma_f32_32x32x16_bf16 v[16:31], v[180:183], v[212:215], v[16:31]
	ds_read_b128 v[204:207], v247 offset:16384
	s_waitcnt lgkmcnt(6)
	v_mfma_f32_32x32x16_bf16 v[0:15], v[180:183], v[216:219], v[0:15]
	ds_read_b128 v[208:211], v248 offset:16384
	s_waitcnt lgkmcnt(6)
	v_mfma_f32_32x32x16_bf16 v[64:79], v[184:187], v[140:143], 0
	ds_read_b128 v[184:187], v249 offset:16384
	s_waitcnt lgkmcnt(6)
	v_mfma_f32_32x32x16_bf16 v[64:79], v[188:191], v[136:139], v[64:79]
	ds_read_b128 v[188:191], v250 offset:8192
	s_waitcnt lgkmcnt(6)
	v_mfma_f32_32x32x16_bf16 v[64:79], v[192:195], v[132:135], v[64:79]
	ds_read_b128 v[192:195], v251 offset:8192
	s_waitcnt lgkmcnt(6)
	v_mfma_f32_32x32x16_bf16 v[64:79], v[196:199], v[128:131], v[64:79]
	ds_read_b128 v[196:199], v252 offset:8192
	s_waitcnt lgkmcnt(6)
	v_mfma_f32_32x32x16_bf16 v[64:79], v[200:203], v[124:127], v[64:79]
	ds_read_b128 v[200:203], v253 offset:8192
	s_waitcnt lgkmcnt(6)
	v_mfma_f32_32x32x16_bf16 v[64:79], v[204:207], v[120:123], v[64:79]
	ds_read_b128 v[204:207], v242 offset:24576
	s_waitcnt lgkmcnt(6)
	v_mfma_f32_32x32x16_bf16 v[64:79], v[208:211], v[116:119], v[64:79]
	ds_read_b128 v[208:211], v243 offset:24576
	s_waitcnt lgkmcnt(6)
	v_mfma_f32_32x32x16_bf16 v[64:79], v[184:187], v[112:115], v[64:79]
	ds_read_b128 v[184:187], v244 offset:24576
	s_waitcnt lgkmcnt(6)
	v_mfma_f32_32x32x16_bf16 v[64:79], v[188:191], v[96:99], v[64:79]
	ds_read_b128 v[188:191], v245 offset:24576
	s_waitcnt lgkmcnt(6)
	v_mfma_f32_32x32x16_bf16 v[64:79], v[192:195], v[100:103], v[64:79]
	ds_read_b128 v[192:195], v246 offset:24576
	s_waitcnt lgkmcnt(6)
	v_mfma_f32_32x32x16_bf16 v[64:79], v[196:199], v[104:107], v[64:79]
	ds_read_b128 v[196:199], v247 offset:24576
	s_waitcnt lgkmcnt(6)
	v_mfma_f32_32x32x16_bf16 v[64:79], v[200:203], v[108:111], v[64:79]
	ds_read_b128 v[200:203], v248 offset:24576
	s_waitcnt lgkmcnt(6)
	v_mfma_f32_32x32x16_bf16 v[80:95], v[204:207], v[140:143], 0
	ds_read_b128 v[204:207], v249 offset:24576
	s_waitcnt lgkmcnt(6)
	v_mfma_f32_32x32x16_bf16 v[80:95], v[208:211], v[136:139], v[80:95]
	ds_read_b128 v[208:211], v250 offset:12288
	s_waitcnt lgkmcnt(6)
	v_mfma_f32_32x32x16_bf16 v[80:95], v[184:187], v[132:135], v[80:95]
	ds_read_b128 v[184:187], v251 offset:12288
	s_waitcnt lgkmcnt(6)
	v_mfma_f32_32x32x16_bf16 v[80:95], v[188:191], v[128:131], v[80:95]
	v_exp_f32_e32 v64, v64
	v_exp_f32_e32 v65, v65
	v_exp_f32_e32 v66, v66
	ds_read_b128 v[188:191], v252 offset:12288
	s_waitcnt lgkmcnt(6)
	v_mfma_f32_32x32x16_bf16 v[80:95], v[192:195], v[124:127], v[80:95]
	v_exp_f32_e32 v67, v67
	v_add_f32_e32 v254, v254, v64
	v_exp_f32_e32 v68, v68
	v_add_f32_e32 v255, v255, v65
	ds_read_b128 v[192:195], v253 offset:12288
	s_waitcnt lgkmcnt(6)
	v_mfma_f32_32x32x16_bf16 v[80:95], v[196:199], v[120:123], v[80:95]
	v_exp_f32_e32 v69, v69
	v_add_f32_e32 v254, v254, v66
	v_exp_f32_e32 v70, v70
	ds_read_b64_tr_b16 v[212:213], v166 offset:0
	ds_read_b64_tr_b16 v[214:215], v166 offset:2048
	s_waitcnt lgkmcnt(7)
	v_mfma_f32_32x32x16_bf16 v[80:95], v[200:203], v[116:119], v[80:95]
	v_add_f32_e32 v255, v255, v67
	v_exp_f32_e32 v71, v71
	v_add_f32_e32 v254, v254, v68
	v_add_f32_e32 v255, v255, v69
	v_add_f32_e32 v254, v254, v70
	ds_read_b64_tr_b16 v[216:217], v166 offset:512
	ds_read_b64_tr_b16 v[218:219], v166 offset:2560
	s_waitcnt lgkmcnt(8)
	v_mfma_f32_32x32x16_bf16 v[80:95], v[204:207], v[112:115], v[80:95]
	v_add_f32_e32 v255, v255, v71
	v_cvt_pk_bf16_f32 v168, v64, v65
	v_cvt_pk_bf16_f32 v170, v68, v69
	v_cvt_pk_bf16_f32 v169, v66, v67
	v_cvt_pk_bf16_f32 v171, v70, v71
	ds_read_b64_tr_b16 v[220:221], v166 offset:1024
	ds_read_b64_tr_b16 v[222:223], v166 offset:3072
	s_waitcnt lgkmcnt(9)
	v_mfma_f32_32x32x16_bf16 v[80:95], v[208:211], v[96:99], v[80:95]
	v_exp_f32_e32 v72, v72
	v_exp_f32_e32 v73, v73
	v_exp_f32_e32 v74, v74
	v_exp_f32_e32 v75, v75
	ds_read_b64_tr_b16 v[224:225], v166 offset:1536
	ds_read_b64_tr_b16 v[226:227], v166 offset:3584
	s_waitcnt lgkmcnt(10)
	v_mfma_f32_32x32x16_bf16 v[80:95], v[184:187], v[100:103], v[80:95]
	v_add_f32_e32 v254, v254, v72
	v_exp_f32_e32 v76, v76
	v_add_f32_e32 v255, v255, v73
	v_exp_f32_e32 v77, v77
	ds_read_b64_tr_b16 v[228:229], v166 offset:4096
	ds_read_b64_tr_b16 v[230:231], v166 offset:6144
	s_waitcnt lgkmcnt(11)
	v_mfma_f32_32x32x16_bf16 v[80:95], v[188:191], v[104:107], v[80:95]
	v_add_f32_e32 v254, v254, v74
	v_exp_f32_e32 v78, v78
	v_add_f32_e32 v255, v255, v75
	v_exp_f32_e32 v79, v79
	v_add_f32_e32 v254, v254, v76
	ds_read_b64_tr_b16 v[232:233], v166 offset:4608
	ds_read_b64_tr_b16 v[234:235], v166 offset:6656
	s_waitcnt lgkmcnt(12)
	v_mfma_f32_32x32x16_bf16 v[80:95], v[192:195], v[108:111], v[80:95]
	v_add_f32_e32 v255, v255, v77
	v_add_f32_e32 v254, v254, v78
	v_add_f32_e32 v255, v255, v79
	v_cvt_pk_bf16_f32 v172, v72, v73
	v_cvt_pk_bf16_f32 v174, v76, v77
	v_cvt_pk_bf16_f32 v173, v74, v75
	v_cvt_pk_bf16_f32 v175, v78, v79
	s_waitcnt vmcnt(0)
	s_barrier
	s_add_i32 s37, s14, 0x8000
	s_cmp_ge_u32 s37, 0xc000
	s_cselect_b32 s18, 0xc000, 0
	s_sub_i32 s37, s37, s18
	ds_read_b64_tr_b16 v[238:239], v166 offset:5120
	ds_read_b64_tr_b16 v[240:241], v166 offset:7168
	s_add_i32 m0, s5, 0x10000
	s_add_u32 s46, s28, s74
	s_addc_u32 s47, s29, s75
	global_load_lds_dwordx4 v154, s[46:47]
	s_waitcnt lgkmcnt(12)
	v_mfma_f32_32x32x16_bf16 v[48:63], v[168:171], v[212:215], v[48:63]
	v_exp_f32_e32 v80, v80
	v_exp_f32_e32 v81, v81
	v_exp_f32_e32 v82, v82
	ds_read_b64_tr_b16 v[212:213], v166 offset:5632
	ds_read_b64_tr_b16 v[214:215], v166 offset:7680
	s_add_i32 m0, s5, 0x12000
	s_add_u32 s46, s28, s76
	s_addc_u32 s47, s29, s77
	global_load_lds_dwordx4 v154, s[46:47]
	s_waitcnt lgkmcnt(12)
	v_mfma_f32_32x32x16_bf16 v[32:47], v[168:171], v[216:219], v[32:47]
	v_exp_f32_e32 v83, v83
	v_add_f32_e32 v254, v254, v80
	v_exp_f32_e32 v84, v84
	v_add_f32_e32 v255, v255, v81
	ds_read_b64_tr_b16 v[216:217], v166 offset:8192
	ds_read_b64_tr_b16 v[218:219], v166 offset:10240
	s_add_i32 m0, s5, s37
	s_add_u32 s46, s28, s78
	s_addc_u32 s47, s29, s79
	global_load_lds_dwordx4 v152, s[46:47]
	s_waitcnt lgkmcnt(12)
	v_mfma_f32_32x32x16_bf16 v[16:31], v[168:171], v[220:223], v[16:31]
	v_exp_f32_e32 v85, v85
	v_add_f32_e32 v254, v254, v82
	v_exp_f32_e32 v86, v86
	ds_read_b64_tr_b16 v[220:221], v166 offset:8704
	ds_read_b64_tr_b16 v[222:223], v166 offset:10752
	s_add_i32 m0, s37, s38
	s_add_u32 s46, s28, s80
	s_addc_u32 s47, s29, s81
	global_load_lds_dwordx4 v152, s[46:47]
	s_waitcnt lgkmcnt(12)
	v_mfma_f32_32x32x16_bf16 v[0:15], v[168:171], v[224:227], v[0:15]
	v_add_f32_e32 v255, v255, v83
	v_exp_f32_e32 v87, v87
	v_add_f32_e32 v254, v254, v84
	v_add_f32_e32 v255, v255, v85
	v_add_f32_e32 v254, v254, v86
	ds_read_b64_tr_b16 v[224:225], v166 offset:9216
	ds_read_b64_tr_b16 v[226:227], v166 offset:11264
	s_add_i32 m0, s5, 0x16000
	s_add_u32 s46, s28, s82
	s_addc_u32 s47, s29, s83
	global_load_lds_dwordx4 v150, s[46:47]
	s_waitcnt lgkmcnt(12)
	v_mfma_f32_32x32x16_bf16 v[48:63], v[172:175], v[228:231], v[48:63]
	v_add_f32_e32 v255, v255, v87
	v_cvt_pk_bf16_f32 v176, v80, v81
	v_cvt_pk_bf16_f32 v178, v84, v85
	v_cvt_pk_bf16_f32 v177, v82, v83
	v_cvt_pk_bf16_f32 v179, v86, v87
	ds_read_b64_tr_b16 v[228:229], v166 offset:9728
	ds_read_b64_tr_b16 v[230:231], v166 offset:11776
	s_waitcnt lgkmcnt(12)
	v_mfma_f32_32x32x16_bf16 v[32:47], v[172:175], v[232:235], v[32:47]
	v_exp_f32_e32 v88, v88
	v_exp_f32_e32 v89, v89
	v_exp_f32_e32 v90, v90
	ds_read_b64_tr_b16 v[232:233], v166 offset:12288
	ds_read_b64_tr_b16 v[234:235], v166 offset:14336
	s_waitcnt lgkmcnt(12)
	v_mfma_f32_32x32x16_bf16 v[16:31], v[172:175], v[238:241], v[16:31]
	v_exp_f32_e32 v91, v91
	v_add_f32_e32 v254, v254, v88
	v_exp_f32_e32 v92, v92
	ds_read_b64_tr_b16 v[238:239], v166 offset:12800
	ds_read_b64_tr_b16 v[240:241], v166 offset:14848
	s_waitcnt lgkmcnt(12)
	v_mfma_f32_32x32x16_bf16 v[0:15], v[172:175], v[212:215], v[0:15]
	v_add_f32_e32 v255, v255, v89
	v_exp_f32_e32 v93, v93
	ds_read_b64_tr_b16 v[212:213], v166 offset:13312
	ds_read_b64_tr_b16 v[214:215], v166 offset:15360
	s_waitcnt lgkmcnt(12)
	v_mfma_f32_32x32x16_bf16 v[48:63], v[176:179], v[216:219], v[48:63]
	v_add_f32_e32 v254, v254, v90
	v_exp_f32_e32 v94, v94
	v_add_f32_e32 v255, v255, v91
	v_exp_f32_e32 v95, v95
	ds_read_b64_tr_b16 v[216:217], v166 offset:13824
	ds_read_b64_tr_b16 v[218:219], v166 offset:15872
	s_waitcnt lgkmcnt(12)
	v_mfma_f32_32x32x16_bf16 v[32:47], v[176:179], v[220:223], v[32:47]
	v_add_f32_e32 v254, v254, v92
	v_add_f32_e32 v255, v255, v93
	v_add_f32_e32 v254, v254, v94
	v_add_f32_e32 v255, v255, v95
	ds_read_b128 v[184:187], v242 offset:0
	s_waitcnt lgkmcnt(11)
	v_mfma_f32_32x32x16_bf16 v[16:31], v[176:179], v[224:227], v[16:31]
	v_cvt_pk_bf16_f32 v180, v88, v89
	v_cvt_pk_bf16_f32 v182, v92, v93
	v_cvt_pk_bf16_f32 v181, v90, v91
	v_cvt_pk_bf16_f32 v183, v94, v95
	ds_read_b128 v[188:191], v243 offset:0
	s_waitcnt lgkmcnt(10)
	v_mfma_f32_32x32x16_bf16 v[0:15], v[176:179], v[228:231], v[0:15]
	s_add_i32 s14, s14, 0x4000
	s_cmp_ge_u32 s14, 0xc000
	s_cselect_b32 s18, 0xc000, 0
	s_sub_i32 s14, s14, s18
	v_add_u32_e32 v166, s14, v165
	ds_read_b128 v[192:195], v244 offset:0
	s_waitcnt lgkmcnt(9)
	v_mfma_f32_32x32x16_bf16 v[48:63], v[180:183], v[232:235], v[48:63]
	ds_read_b128 v[196:199], v245 offset:0
	s_waitcnt lgkmcnt(8)
	v_mfma_f32_32x32x16_bf16 v[32:47], v[180:183], v[238:241], v[32:47]
	ds_read_b128 v[200:203], v246 offset:0
	s_waitcnt lgkmcnt(7)
	v_mfma_f32_32x32x16_bf16 v[16:31], v[180:183], v[212:215], v[16:31]
	ds_read_b128 v[204:207], v247 offset:0
	s_waitcnt lgkmcnt(6)
	v_mfma_f32_32x32x16_bf16 v[0:15], v[180:183], v[216:219], v[0:15]
	ds_read_b128 v[208:211], v248 offset:0
	s_waitcnt lgkmcnt(6)
	v_mfma_f32_32x32x16_bf16 v[64:79], v[184:187], v[140:143], 0
	ds_read_b128 v[184:187], v249 offset:0
	s_waitcnt lgkmcnt(6)
	v_mfma_f32_32x32x16_bf16 v[64:79], v[188:191], v[136:139], v[64:79]
	ds_read_b128 v[188:191], v250 offset:0
	s_waitcnt lgkmcnt(6)
	v_mfma_f32_32x32x16_bf16 v[64:79], v[192:195], v[132:135], v[64:79]
	ds_read_b128 v[192:195], v251 offset:0
	s_waitcnt lgkmcnt(6)
	v_mfma_f32_32x32x16_bf16 v[64:79], v[196:199], v[128:131], v[64:79]
	ds_read_b128 v[196:199], v252 offset:0
	s_waitcnt lgkmcnt(6)
	v_mfma_f32_32x32x16_bf16 v[64:79], v[200:203], v[124:127], v[64:79]
	ds_read_b128 v[200:203], v253 offset:0
	s_waitcnt lgkmcnt(6)
	v_mfma_f32_32x32x16_bf16 v[64:79], v[204:207], v[120:123], v[64:79]
	ds_read_b128 v[204:207], v242 offset:8192
	s_waitcnt lgkmcnt(6)
	v_mfma_f32_32x32x16_bf16 v[64:79], v[208:211], v[116:119], v[64:79]
	ds_read_b128 v[208:211], v243 offset:8192
	s_waitcnt lgkmcnt(6)
	v_mfma_f32_32x32x16_bf16 v[64:79], v[184:187], v[112:115], v[64:79]
	ds_read_b128 v[184:187], v244 offset:8192
	s_waitcnt lgkmcnt(6)
	v_mfma_f32_32x32x16_bf16 v[64:79], v[188:191], v[96:99], v[64:79]
	ds_read_b128 v[188:191], v245 offset:8192
	s_waitcnt lgkmcnt(6)
	v_mfma_f32_32x32x16_bf16 v[64:79], v[192:195], v[100:103], v[64:79]
	ds_read_b128 v[192:195], v246 offset:8192
	s_waitcnt lgkmcnt(6)
	v_mfma_f32_32x32x16_bf16 v[64:79], v[196:199], v[104:107], v[64:79]
	ds_read_b128 v[196:199], v247 offset:8192
	s_waitcnt lgkmcnt(6)
	v_mfma_f32_32x32x16_bf16 v[64:79], v[200:203], v[108:111], v[64:79]
	ds_read_b128 v[200:203], v248 offset:8192
	s_waitcnt lgkmcnt(6)
	v_mfma_f32_32x32x16_bf16 v[80:95], v[204:207], v[140:143], 0
	ds_read_b128 v[204:207], v249 offset:8192
	s_waitcnt lgkmcnt(6)
	v_mfma_f32_32x32x16_bf16 v[80:95], v[208:211], v[136:139], v[80:95]
	ds_read_b128 v[208:211], v250 offset:4096
	s_waitcnt lgkmcnt(6)
	v_mfma_f32_32x32x16_bf16 v[80:95], v[184:187], v[132:135], v[80:95]
	ds_read_b128 v[184:187], v251 offset:4096
	s_waitcnt lgkmcnt(6)
	v_mfma_f32_32x32x16_bf16 v[80:95], v[188:191], v[128:131], v[80:95]
	v_exp_f32_e32 v64, v64
	v_exp_f32_e32 v65, v65
	v_exp_f32_e32 v66, v66
	ds_read_b128 v[188:191], v252 offset:4096
	s_waitcnt lgkmcnt(6)
	v_mfma_f32_32x32x16_bf16 v[80:95], v[192:195], v[124:127], v[80:95]
	v_exp_f32_e32 v67, v67
	v_add_f32_e32 v254, v254, v64
	v_exp_f32_e32 v68, v68
	v_add_f32_e32 v255, v255, v65
	ds_read_b128 v[192:195], v253 offset:4096
	s_waitcnt lgkmcnt(6)
	v_mfma_f32_32x32x16_bf16 v[80:95], v[196:199], v[120:123], v[80:95]
	v_exp_f32_e32 v69, v69
	v_add_f32_e32 v254, v254, v66
	v_exp_f32_e32 v70, v70
	ds_read_b64_tr_b16 v[212:213], v166 offset:0
	ds_read_b64_tr_b16 v[214:215], v166 offset:2048
	s_waitcnt lgkmcnt(7)
	v_mfma_f32_32x32x16_bf16 v[80:95], v[200:203], v[116:119], v[80:95]
	v_add_f32_e32 v255, v255, v67
	v_exp_f32_e32 v71, v71
	v_add_f32_e32 v254, v254, v68
	v_add_f32_e32 v255, v255, v69
	v_add_f32_e32 v254, v254, v70
	ds_read_b64_tr_b16 v[216:217], v166 offset:512
	ds_read_b64_tr_b16 v[218:219], v166 offset:2560
	s_waitcnt lgkmcnt(8)
	v_mfma_f32_32x32x16_bf16 v[80:95], v[204:207], v[112:115], v[80:95]
	v_add_f32_e32 v255, v255, v71
	v_cvt_pk_bf16_f32 v168, v64, v65
	v_cvt_pk_bf16_f32 v170, v68, v69
	v_cvt_pk_bf16_f32 v169, v66, v67
	v_cvt_pk_bf16_f32 v171, v70, v71
	ds_read_b64_tr_b16 v[220:221], v166 offset:1024
	ds_read_b64_tr_b16 v[222:223], v166 offset:3072
	s_waitcnt lgkmcnt(9)
	v_mfma_f32_32x32x16_bf16 v[80:95], v[208:211], v[96:99], v[80:95]
	v_exp_f32_e32 v72, v72
	v_exp_f32_e32 v73, v73
	v_exp_f32_e32 v74, v74
	v_exp_f32_e32 v75, v75
	ds_read_b64_tr_b16 v[224:225], v166 offset:1536
	ds_read_b64_tr_b16 v[226:227], v166 offset:3584
	s_waitcnt lgkmcnt(10)
	v_mfma_f32_32x32x16_bf16 v[80:95], v[184:187], v[100:103], v[80:95]
	v_add_f32_e32 v254, v254, v72
	v_exp_f32_e32 v76, v76
	v_add_f32_e32 v255, v255, v73
	v_exp_f32_e32 v77, v77
	ds_read_b64_tr_b16 v[228:229], v166 offset:4096
	ds_read_b64_tr_b16 v[230:231], v166 offset:6144
	s_waitcnt lgkmcnt(11)
	v_mfma_f32_32x32x16_bf16 v[80:95], v[188:191], v[104:107], v[80:95]
	v_add_f32_e32 v254, v254, v74
	v_exp_f32_e32 v78, v78
	v_add_f32_e32 v255, v255, v75
	v_exp_f32_e32 v79, v79
	v_add_f32_e32 v254, v254, v76
	ds_read_b64_tr_b16 v[232:233], v166 offset:4608
	ds_read_b64_tr_b16 v[234:235], v166 offset:6656
	s_waitcnt lgkmcnt(12)
	v_mfma_f32_32x32x16_bf16 v[80:95], v[192:195], v[108:111], v[80:95]
	v_add_f32_e32 v255, v255, v77
	v_add_f32_e32 v254, v254, v78
	v_add_f32_e32 v255, v255, v79
	v_cvt_pk_bf16_f32 v172, v72, v73
	v_cvt_pk_bf16_f32 v174, v76, v77
	v_cvt_pk_bf16_f32 v173, v74, v75
	v_cvt_pk_bf16_f32 v175, v78, v79
	v_add_u32_e32 v150, s84, v150
	v_add_u32_e32 v152, s86, v152
	v_add_u32_e32 v154, s86, v154
	s_sub_i32 s15, s15, 1
	s_cmp_lg_u32 s15, 0
	s_cbranch_scc1 .Lmla_loop
	s_waitcnt vmcnt(0)
	s_barrier
	ds_read_b64_tr_b16 v[238:239], v166 offset:5120
	ds_read_b64_tr_b16 v[240:241], v166 offset:7168
	s_waitcnt lgkmcnt(12)
	v_mfma_f32_32x32x16_bf16 v[48:63], v[168:171], v[212:215], v[48:63]
	v_exp_f32_e32 v80, v80
	v_exp_f32_e32 v81, v81
	v_exp_f32_e32 v82, v82
	ds_read_b64_tr_b16 v[212:213], v166 offset:5632
	ds_read_b64_tr_b16 v[214:215], v166 offset:7680
	s_waitcnt lgkmcnt(12)
	v_mfma_f32_32x32x16_bf16 v[32:47], v[168:171], v[216:219], v[32:47]
	v_exp_f32_e32 v83, v83
	v_add_f32_e32 v254, v254, v80
	v_exp_f32_e32 v84, v84
	v_add_f32_e32 v255, v255, v81
	ds_read_b64_tr_b16 v[216:217], v166 offset:8192
	ds_read_b64_tr_b16 v[218:219], v166 offset:10240
	s_waitcnt lgkmcnt(12)
	v_mfma_f32_32x32x16_bf16 v[16:31], v[168:171], v[220:223], v[16:31]
	v_exp_f32_e32 v85, v85
	v_add_f32_e32 v254, v254, v82
	v_exp_f32_e32 v86, v86
	ds_read_b64_tr_b16 v[220:221], v166 offset:8704
	ds_read_b64_tr_b16 v[222:223], v166 offset:10752
	s_waitcnt lgkmcnt(12)
	v_mfma_f32_32x32x16_bf16 v[0:15], v[168:171], v[224:227], v[0:15]
	v_add_f32_e32 v255, v255, v83
	v_exp_f32_e32 v87, v87
	v_add_f32_e32 v254, v254, v84
	v_add_f32_e32 v255, v255, v85
	v_add_f32_e32 v254, v254, v86
	ds_read_b64_tr_b16 v[224:225], v166 offset:9216
	ds_read_b64_tr_b16 v[226:227], v166 offset:11264
	s_waitcnt lgkmcnt(12)
	v_mfma_f32_32x32x16_bf16 v[48:63], v[172:175], v[228:231], v[48:63]
	v_add_f32_e32 v255, v255, v87
	v_cvt_pk_bf16_f32 v176, v80, v81
	v_cvt_pk_bf16_f32 v178, v84, v85
	v_cvt_pk_bf16_f32 v177, v82, v83
	v_cvt_pk_bf16_f32 v179, v86, v87
	ds_read_b64_tr_b16 v[228:229], v166 offset:9728
	ds_read_b64_tr_b16 v[230:231], v166 offset:11776
	s_waitcnt lgkmcnt(12)
	v_mfma_f32_32x32x16_bf16 v[32:47], v[172:175], v[232:235], v[32:47]
	v_exp_f32_e32 v88, v88
	v_exp_f32_e32 v89, v89
	v_exp_f32_e32 v90, v90
	ds_read_b64_tr_b16 v[232:233], v166 offset:12288
	ds_read_b64_tr_b16 v[234:235], v166 offset:14336
	s_waitcnt lgkmcnt(12)
	v_mfma_f32_32x32x16_bf16 v[16:31], v[172:175], v[238:241], v[16:31]
	v_exp_f32_e32 v91, v91
	v_add_f32_e32 v254, v254, v88
	v_exp_f32_e32 v92, v92
	ds_read_b64_tr_b16 v[238:239], v166 offset:12800
	ds_read_b64_tr_b16 v[240:241], v166 offset:14848
	s_waitcnt lgkmcnt(12)
	v_mfma_f32_32x32x16_bf16 v[0:15], v[172:175], v[212:215], v[0:15]
	v_add_f32_e32 v255, v255, v89
	v_exp_f32_e32 v93, v93
	ds_read_b64_tr_b16 v[212:213], v166 offset:13312
	ds_read_b64_tr_b16 v[214:215], v166 offset:15360
	s_waitcnt lgkmcnt(12)
	v_mfma_f32_32x32x16_bf16 v[48:63], v[176:179], v[216:219], v[48:63]
	v_add_f32_e32 v254, v254, v90
	v_exp_f32_e32 v94, v94
	v_add_f32_e32 v255, v255, v91
	v_exp_f32_e32 v95, v95
	ds_read_b64_tr_b16 v[216:217], v166 offset:13824
	ds_read_b64_tr_b16 v[218:219], v166 offset:15872
	s_waitcnt lgkmcnt(12)
	v_mfma_f32_32x32x16_bf16 v[32:47], v[176:179], v[220:223], v[32:47]
	v_add_f32_e32 v254, v254, v92
	v_add_f32_e32 v255, v255, v93
	v_add_f32_e32 v254, v254, v94
	v_add_f32_e32 v255, v255, v95
	ds_read_b128 v[184:187], v242 offset:16384
	s_waitcnt lgkmcnt(11)
	v_mfma_f32_32x32x16_bf16 v[16:31], v[176:179], v[224:227], v[16:31]
	v_cvt_pk_bf16_f32 v180, v88, v89
	v_cvt_pk_bf16_f32 v182, v92, v93
	v_cvt_pk_bf16_f32 v181, v90, v91
	v_cvt_pk_bf16_f32 v183, v94, v95
	ds_read_b128 v[188:191], v243 offset:16384
	s_waitcnt lgkmcnt(10)
	v_mfma_f32_32x32x16_bf16 v[0:15], v[176:179], v[228:231], v[0:15]
	s_add_i32 s14, s14, 0x4000
	s_cmp_ge_u32 s14, 0xc000
	s_cselect_b32 s18, 0xc000, 0
	s_sub_i32 s14, s14, s18
	v_add_u32_e32 v166, s14, v165
	ds_read_b128 v[192:195], v244 offset:16384
	s_waitcnt lgkmcnt(9)
	v_mfma_f32_32x32x16_bf16 v[48:63], v[180:183], v[232:235], v[48:63]
	ds_read_b128 v[196:199], v245 offset:16384
	s_waitcnt lgkmcnt(8)
	v_mfma_f32_32x32x16_bf16 v[32:47], v[180:183], v[238:241], v[32:47]
	ds_read_b128 v[200:203], v246 offset:16384
	s_waitcnt lgkmcnt(7)
	v_mfma_f32_32x32x16_bf16 v[16:31], v[180:183], v[212:215], v[16:31]
	ds_read_b128 v[204:207], v247 offset:16384
	s_waitcnt lgkmcnt(6)
	v_mfma_f32_32x32x16_bf16 v[0:15], v[180:183], v[216:219], v[0:15]
	ds_read_b128 v[208:211], v248 offset:16384
	s_waitcnt lgkmcnt(6)
	v_mfma_f32_32x32x16_bf16 v[64:79], v[184:187], v[140:143], 0
	ds_read_b128 v[184:187], v249 offset:16384
	s_waitcnt lgkmcnt(6)
	v_mfma_f32_32x32x16_bf16 v[64:79], v[188:191], v[136:139], v[64:79]
	ds_read_b128 v[188:191], v250 offset:8192
	s_waitcnt lgkmcnt(6)
	v_mfma_f32_32x32x16_bf16 v[64:79], v[192:195], v[132:135], v[64:79]
	ds_read_b128 v[192:195], v251 offset:8192
	s_waitcnt lgkmcnt(6)
	v_mfma_f32_32x32x16_bf16 v[64:79], v[196:199], v[128:131], v[64:79]
	ds_read_b128 v[196:199], v252 offset:8192
	s_waitcnt lgkmcnt(6)
	v_mfma_f32_32x32x16_bf16 v[64:79], v[200:203], v[124:127], v[64:79]
	ds_read_b128 v[200:203], v253 offset:8192
	s_waitcnt lgkmcnt(6)
	v_mfma_f32_32x32x16_bf16 v[64:79], v[204:207], v[120:123], v[64:79]
	ds_read_b128 v[204:207], v242 offset:24576
	s_waitcnt lgkmcnt(6)
	v_mfma_f32_32x32x16_bf16 v[64:79], v[208:211], v[116:119], v[64:79]
	ds_read_b128 v[208:211], v243 offset:24576
	s_waitcnt lgkmcnt(6)
	v_mfma_f32_32x32x16_bf16 v[64:79], v[184:187], v[112:115], v[64:79]
	ds_read_b128 v[184:187], v244 offset:24576
	s_waitcnt lgkmcnt(6)
	v_mfma_f32_32x32x16_bf16 v[64:79], v[188:191], v[96:99], v[64:79]
	ds_read_b128 v[188:191], v245 offset:24576
	s_waitcnt lgkmcnt(6)
	v_mfma_f32_32x32x16_bf16 v[64:79], v[192:195], v[100:103], v[64:79]
	ds_read_b128 v[192:195], v246 offset:24576
	s_waitcnt lgkmcnt(6)
	v_mfma_f32_32x32x16_bf16 v[64:79], v[196:199], v[104:107], v[64:79]
	ds_read_b128 v[196:199], v247 offset:24576
	s_waitcnt lgkmcnt(6)
	v_mfma_f32_32x32x16_bf16 v[64:79], v[200:203], v[108:111], v[64:79]
	ds_read_b128 v[200:203], v248 offset:24576
	s_waitcnt lgkmcnt(6)
	v_mfma_f32_32x32x16_bf16 v[80:95], v[204:207], v[140:143], 0
	ds_read_b128 v[204:207], v249 offset:24576
	s_waitcnt lgkmcnt(6)
	v_mfma_f32_32x32x16_bf16 v[80:95], v[208:211], v[136:139], v[80:95]
	ds_read_b128 v[208:211], v250 offset:12288
	s_waitcnt lgkmcnt(6)
	v_mfma_f32_32x32x16_bf16 v[80:95], v[184:187], v[132:135], v[80:95]
	ds_read_b128 v[184:187], v251 offset:12288
	s_waitcnt lgkmcnt(6)
	v_mfma_f32_32x32x16_bf16 v[80:95], v[188:191], v[128:131], v[80:95]
	v_exp_f32_e32 v64, v64
	v_exp_f32_e32 v65, v65
	v_exp_f32_e32 v66, v66
	ds_read_b128 v[188:191], v252 offset:12288
	s_waitcnt lgkmcnt(6)
	v_mfma_f32_32x32x16_bf16 v[80:95], v[192:195], v[124:127], v[80:95]
	v_exp_f32_e32 v67, v67
	v_add_f32_e32 v254, v254, v64
	v_exp_f32_e32 v68, v68
	v_add_f32_e32 v255, v255, v65
	ds_read_b128 v[192:195], v253 offset:12288
	s_waitcnt lgkmcnt(6)
	v_mfma_f32_32x32x16_bf16 v[80:95], v[196:199], v[120:123], v[80:95]
	v_exp_f32_e32 v69, v69
	v_add_f32_e32 v254, v254, v66
	v_exp_f32_e32 v70, v70
	ds_read_b64_tr_b16 v[212:213], v166 offset:0
	ds_read_b64_tr_b16 v[214:215], v166 offset:2048
	s_waitcnt lgkmcnt(7)
	v_mfma_f32_32x32x16_bf16 v[80:95], v[200:203], v[116:119], v[80:95]
	v_add_f32_e32 v255, v255, v67
	v_exp_f32_e32 v71, v71
	v_add_f32_e32 v254, v254, v68
	v_add_f32_e32 v255, v255, v69
	v_add_f32_e32 v254, v254, v70
	ds_read_b64_tr_b16 v[216:217], v166 offset:512
	ds_read_b64_tr_b16 v[218:219], v166 offset:2560
	s_waitcnt lgkmcnt(8)
	v_mfma_f32_32x32x16_bf16 v[80:95], v[204:207], v[112:115], v[80:95]
	v_add_f32_e32 v255, v255, v71
	v_cvt_pk_bf16_f32 v168, v64, v65
	v_cvt_pk_bf16_f32 v170, v68, v69
	v_cvt_pk_bf16_f32 v169, v66, v67
	v_cvt_pk_bf16_f32 v171, v70, v71
	ds_read_b64_tr_b16 v[220:221], v166 offset:1024
	ds_read_b64_tr_b16 v[222:223], v166 offset:3072
	s_waitcnt lgkmcnt(9)
	v_mfma_f32_32x32x16_bf16 v[80:95], v[208:211], v[96:99], v[80:95]
	v_exp_f32_e32 v72, v72
	v_exp_f32_e32 v73, v73
	v_exp_f32_e32 v74, v74
	v_exp_f32_e32 v75, v75
	ds_read_b64_tr_b16 v[224:225], v166 offset:1536
	ds_read_b64_tr_b16 v[226:227], v166 offset:3584
	s_waitcnt lgkmcnt(10)
	v_mfma_f32_32x32x16_bf16 v[80:95], v[184:187], v[100:103], v[80:95]
	v_add_f32_e32 v254, v254, v72
	v_exp_f32_e32 v76, v76
	v_add_f32_e32 v255, v255, v73
	v_exp_f32_e32 v77, v77
	ds_read_b64_tr_b16 v[228:229], v166 offset:4096
	ds_read_b64_tr_b16 v[230:231], v166 offset:6144
	s_waitcnt lgkmcnt(11)
	v_mfma_f32_32x32x16_bf16 v[80:95], v[188:191], v[104:107], v[80:95]
	v_add_f32_e32 v254, v254, v74
	v_exp_f32_e32 v78, v78
	v_add_f32_e32 v255, v255, v75
	v_exp_f32_e32 v79, v79
	v_add_f32_e32 v254, v254, v76
	ds_read_b64_tr_b16 v[232:233], v166 offset:4608
	ds_read_b64_tr_b16 v[234:235], v166 offset:6656
	s_waitcnt lgkmcnt(12)
	v_mfma_f32_32x32x16_bf16 v[80:95], v[192:195], v[108:111], v[80:95]
	v_add_f32_e32 v255, v255, v77
	v_add_f32_e32 v254, v254, v78
	v_add_f32_e32 v255, v255, v79
	v_cvt_pk_bf16_f32 v172, v72, v73
	v_cvt_pk_bf16_f32 v174, v76, v77
	v_cvt_pk_bf16_f32 v173, v74, v75
	v_cvt_pk_bf16_f32 v175, v78, v79
	ds_read_b64_tr_b16 v[238:239], v166 offset:5120
	ds_read_b64_tr_b16 v[240:241], v166 offset:7168
	s_waitcnt lgkmcnt(12)
	v_mfma_f32_32x32x16_bf16 v[48:63], v[168:171], v[212:215], v[48:63]
	s_nop 0
	v_exp_f32_e32 v80, v80
	v_exp_f32_e32 v81, v81
	v_exp_f32_e32 v82, v82
	ds_read_b64_tr_b16 v[212:213], v166 offset:5632
	ds_read_b64_tr_b16 v[214:215], v166 offset:7680
	s_waitcnt lgkmcnt(12)
	v_mfma_f32_32x32x16_bf16 v[32:47], v[168:171], v[216:219], v[32:47]
	v_exp_f32_e32 v83, v83
	v_add_f32_e32 v254, v254, v80
	v_exp_f32_e32 v84, v84
	v_add_f32_e32 v255, v255, v81
	ds_read_b64_tr_b16 v[216:217], v166 offset:8192
	ds_read_b64_tr_b16 v[218:219], v166 offset:10240
	s_waitcnt lgkmcnt(12)
	v_mfma_f32_32x32x16_bf16 v[16:31], v[168:171], v[220:223], v[16:31]
	v_exp_f32_e32 v85, v85
	v_add_f32_e32 v254, v254, v82
	v_exp_f32_e32 v86, v86
	ds_read_b64_tr_b16 v[220:221], v166 offset:8704
	ds_read_b64_tr_b16 v[222:223], v166 offset:10752
	s_waitcnt lgkmcnt(12)
	v_mfma_f32_32x32x16_bf16 v[0:15], v[168:171], v[224:227], v[0:15]
	v_add_f32_e32 v255, v255, v83
	v_exp_f32_e32 v87, v87
	v_add_f32_e32 v254, v254, v84
	v_add_f32_e32 v255, v255, v85
	v_add_f32_e32 v254, v254, v86
	ds_read_b64_tr_b16 v[224:225], v166 offset:9216
	ds_read_b64_tr_b16 v[226:227], v166 offset:11264
	s_waitcnt lgkmcnt(12)
	v_mfma_f32_32x32x16_bf16 v[48:63], v[172:175], v[228:231], v[48:63]
	v_add_f32_e32 v255, v255, v87
	v_cvt_pk_bf16_f32 v176, v80, v81
	v_cvt_pk_bf16_f32 v178, v84, v85
	v_cvt_pk_bf16_f32 v177, v82, v83
	v_cvt_pk_bf16_f32 v179, v86, v87
	ds_read_b64_tr_b16 v[228:229], v166 offset:9728
	ds_read_b64_tr_b16 v[230:231], v166 offset:11776
	s_waitcnt lgkmcnt(12)
	v_mfma_f32_32x32x16_bf16 v[32:47], v[172:175], v[232:235], v[32:47]
	v_exp_f32_e32 v88, v88
	v_exp_f32_e32 v89, v89
	v_exp_f32_e32 v90, v90
	ds_read_b64_tr_b16 v[232:233], v166 offset:12288
	ds_read_b64_tr_b16 v[234:235], v166 offset:14336
	s_waitcnt lgkmcnt(12)
	v_mfma_f32_32x32x16_bf16 v[16:31], v[172:175], v[238:241], v[16:31]
	v_exp_f32_e32 v91, v91
	v_add_f32_e32 v254, v254, v88
	v_exp_f32_e32 v92, v92
	ds_read_b64_tr_b16 v[238:239], v166 offset:12800
	ds_read_b64_tr_b16 v[240:241], v166 offset:14848
	s_waitcnt lgkmcnt(12)
	v_mfma_f32_32x32x16_bf16 v[0:15], v[172:175], v[212:215], v[0:15]
	v_add_f32_e32 v255, v255, v89
	v_exp_f32_e32 v93, v93
	ds_read_b64_tr_b16 v[212:213], v166 offset:13312
	ds_read_b64_tr_b16 v[214:215], v166 offset:15360
	s_waitcnt lgkmcnt(12)
	v_mfma_f32_32x32x16_bf16 v[48:63], v[176:179], v[216:219], v[48:63]
	v_add_f32_e32 v254, v254, v90
	v_exp_f32_e32 v94, v94
	v_add_f32_e32 v255, v255, v91
	v_exp_f32_e32 v95, v95
	ds_read_b64_tr_b16 v[216:217], v166 offset:13824
	ds_read_b64_tr_b16 v[218:219], v166 offset:15872
	s_waitcnt lgkmcnt(12)
	v_mfma_f32_32x32x16_bf16 v[32:47], v[176:179], v[220:223], v[32:47]
	v_add_f32_e32 v254, v254, v92
	v_add_f32_e32 v255, v255, v93
	v_add_f32_e32 v254, v254, v94
	v_add_f32_e32 v255, v255, v95
	s_waitcnt lgkmcnt(10)
	v_mfma_f32_32x32x16_bf16 v[16:31], v[176:179], v[224:227], v[16:31]
	v_cvt_pk_bf16_f32 v180, v88, v89
	v_cvt_pk_bf16_f32 v182, v92, v93
	v_cvt_pk_bf16_f32 v181, v90, v91
	v_cvt_pk_bf16_f32 v183, v94, v95
	s_waitcnt lgkmcnt(8)
	v_mfma_f32_32x32x16_bf16 v[0:15], v[176:179], v[228:231], v[0:15]
	s_waitcnt lgkmcnt(6)
	v_mfma_f32_32x32x16_bf16 v[48:63], v[180:183], v[232:235], v[48:63]
	s_waitcnt lgkmcnt(4)
	v_mfma_f32_32x32x16_bf16 v[32:47], v[180:183], v[238:241], v[32:47]
	s_waitcnt lgkmcnt(2)
	v_mfma_f32_32x32x16_bf16 v[16:31], v[180:183], v[212:215], v[16:31]
	s_waitcnt lgkmcnt(0)
	v_mfma_f32_32x32x16_bf16 v[0:15], v[180:183], v[216:219], v[0:15]
	v_add_f32_e32 v112, v254, v255
	v_mov_b32_e32 v113, 0
	v_mov_b32_e32 v115, 0
	v_mov_b32_e32 v114, v112
	v_mov_b32_e32 v146, 0
	s_nop 0
	v_permlane32_swap_b32_e32 v112, v114
	s_and_b32 s0, s0, 0x3fffffc0
	s_lshl_b32 s0, s0, 2
	s_add_i32 s5, s0, 0
	s_add_i32 s5, s5, 0x18000
	s_setprio 0
	v_cmp_gt_u32_e32 vcc, 32, v149
	s_and_saveexec_b64 s[0:1], vcc
	s_cbranch_execz .LBB0_781
	v_pk_add_f32 v[64:65], v[112:113], v[114:115]
	v_lshl_add_u32 v66, v162, 2, s5
	v_add_f32_e32 v64, v146, v64
	v_add_f32_e32 v64, v64, v65
	ds_write_b32 v66, v64
	s_branch .LBB0_781
